# LDS bank conflicts: intra-chunk kz transposition maps lanes to 32 consecutive dk x 2 token groups (was 16 lanes per bank on the 2-byte LDS writes; global fetch now 1 KB contiguous per wave)
# speedup vs baseline: 1.0214x; 1.0161x over previous
.LBB0_1161:
	v_and_b32_e32 v4, 31, v3
	v_lshrrev_b32_e32 v7, 5, v3
	v_lshlrev_b32_e32 v7, 3, v7
	v_lshrrev_b32_e32 v8, 5, v4
	v_mul_u32_u24_e32 v8, 0x42, v8
	v_add_u32_e32 v8, s90, v8
	v_lshlrev_b32_e32 v8, 13, v8
	v_bfe_u32 v9, v4, 4, 1
	v_lshlrev_b32_e32 v9, 2, v9
	v_lshrrev_b32_e32 v10, 5, v7
	v_add_u32_e32 v9, v9, v10
	v_lshl_add_u32 v8, v9, 10, v8
	v_bfe_u32 v9, v7, 3, 2
	v_lshlrev_b32_e32 v9, 4, v9
	v_and_b32_e32 v10, 15, v4
	v_add_u32_e32 v9, v9, v10
	v_lshl_add_u32 v8, v9, 4, v8
	v_mov_b32_e32 v9, 0
	v_lshl_add_u64 v[8:9], s[98:99], 0, v[8:9]
	v_lshlrev_b32_e32 v0, 1, v4
	v_mul_u32_u24_e32 v4, 0x210, v7
	v_add3_u32 v0, 16, v0, v4
	s_movk_i32 s91, 0xdff
	s_mov_b32 s100, 0x84000
	s_mov_b32 s101, 0
	global_load_dwordx4 v[124:127], v[8:9], off
	v_lshl_add_u64 v[8:9], v[8:9], 0, s[100:101]
	global_load_dwordx4 v[128:131], v[8:9], off
	v_lshl_add_u64 v[8:9], v[8:9], 0, s[100:101]
	global_load_dwordx4 v[132:135], v[8:9], off
	v_lshl_add_u64 v[8:9], v[8:9], 0, s[100:101]
	global_load_dwordx4 v[136:139], v[8:9], off
	v_lshl_add_u64 v[8:9], v[8:9], 0, s[100:101]
	global_load_dwordx4 v[140:143], v[8:9], off
	v_lshl_add_u64 v[8:9], v[8:9], 0, s[100:101]
	global_load_dwordx4 v[144:147], v[8:9], off
	v_lshl_add_u64 v[8:9], v[8:9], 0, s[100:101]
	global_load_dwordx4 v[148:151], v[8:9], off
	v_lshl_add_u64 v[8:9], v[8:9], 0, s[100:101]
	global_load_dwordx4 v[152:155], v[8:9], off
	s_waitcnt vmcnt(7)
	ds_write_b16 v0, v124
	ds_write_b16_d16_hi v0, v124 offset:528
	ds_write_b16 v0, v125 offset:1056
	ds_write_b16_d16_hi v0, v125 offset:1584
	ds_write_b16 v0, v126 offset:2112
	ds_write_b16_d16_hi v0, v126 offset:2640
	ds_write_b16 v0, v127 offset:3168
	ds_write_b16_d16_hi v0, v127 offset:3696
	s_waitcnt vmcnt(6)
	ds_write_b16 v0, v128 offset:64
	ds_write_b16_d16_hi v0, v128 offset:592
	ds_write_b16 v0, v129 offset:1120
	ds_write_b16_d16_hi v0, v129 offset:1648
	ds_write_b16 v0, v130 offset:2176
	ds_write_b16_d16_hi v0, v130 offset:2704
	ds_write_b16 v0, v131 offset:3232
	ds_write_b16_d16_hi v0, v131 offset:3760
	s_waitcnt vmcnt(5)
	ds_write_b16 v0, v132 offset:128
	ds_write_b16_d16_hi v0, v132 offset:656
	ds_write_b16 v0, v133 offset:1184
	ds_write_b16_d16_hi v0, v133 offset:1712
	ds_write_b16 v0, v134 offset:2240
	ds_write_b16_d16_hi v0, v134 offset:2768
	ds_write_b16 v0, v135 offset:3296
	ds_write_b16_d16_hi v0, v135 offset:3824
	s_waitcnt vmcnt(4)
	ds_write_b16 v0, v136 offset:192
	ds_write_b16_d16_hi v0, v136 offset:720
	ds_write_b16 v0, v137 offset:1248
	ds_write_b16_d16_hi v0, v137 offset:1776
	ds_write_b16 v0, v138 offset:2304
	ds_write_b16_d16_hi v0, v138 offset:2832
	ds_write_b16 v0, v139 offset:3360
	ds_write_b16_d16_hi v0, v139 offset:3888
	s_waitcnt vmcnt(3)
	ds_write_b16 v0, v140 offset:256
	ds_write_b16_d16_hi v0, v140 offset:784
	ds_write_b16 v0, v141 offset:1312
	ds_write_b16_d16_hi v0, v141 offset:1840
	ds_write_b16 v0, v142 offset:2368
	ds_write_b16_d16_hi v0, v142 offset:2896
	ds_write_b16 v0, v143 offset:3424
	ds_write_b16_d16_hi v0, v143 offset:3952
	s_waitcnt vmcnt(2)
	ds_write_b16 v0, v144 offset:320
	ds_write_b16_d16_hi v0, v144 offset:848
	ds_write_b16 v0, v145 offset:1376
	ds_write_b16_d16_hi v0, v145 offset:1904
	ds_write_b16 v0, v146 offset:2432
	ds_write_b16_d16_hi v0, v146 offset:2960
	ds_write_b16 v0, v147 offset:3488
	ds_write_b16_d16_hi v0, v147 offset:4016
	s_waitcnt vmcnt(1)
	ds_write_b16 v0, v148 offset:384
	ds_write_b16_d16_hi v0, v148 offset:912
	ds_write_b16 v0, v149 offset:1440
	ds_write_b16_d16_hi v0, v149 offset:1968
	ds_write_b16 v0, v150 offset:2496
	ds_write_b16_d16_hi v0, v150 offset:3024
	ds_write_b16 v0, v151 offset:3552
	ds_write_b16_d16_hi v0, v151 offset:4080
	s_waitcnt vmcnt(0)
	ds_write_b16 v0, v152 offset:448
	ds_write_b16_d16_hi v0, v152 offset:976
	ds_write_b16 v0, v153 offset:1504
	ds_write_b16_d16_hi v0, v153 offset:2032
	ds_write_b16 v0, v154 offset:2560
	ds_write_b16_d16_hi v0, v154 offset:3088
	ds_write_b16 v0, v155 offset:3616
	ds_write_b16_d16_hi v0, v155 offset:4144
	s_or_b64 exec, exec, s[86:87]
	v_mov_b64_e32 v[4:5], s[72:73]
	v_mov_b64_e32 v[2:3], s[82:83]
	s_branch .LBB0_1156
